# as v27 but the shared rope-key (KPE) LDS-DMA pieces are issued by waves 4-7 instead of waves 0-3
# speedup vs baseline: 1.0076x; 1.0076x over previous
; #define ATT_DMA(t, sk, sv) do { glds16(ksrc + (long)(t) * 64 * a.ldk, (unsigned)__builtin_amdgcn_readfirstlane(kdst + (sk) * KSLOT)); \
;         if (MODE == 0 && wid < 4) glds16(kpsrc + (long)(t) * 64 * 32, (unsigned)__builtin_amdgcn_readfirstlane(kpdst + (sk) * KSLOT)); \
;         glds16(vsrc + (long)(t) * 64 * a.ldv, (unsigned)__builtin_amdgcn_readfirstlane(vdst + (sv) * VSLOT)); } while (0)
; #define ATT_WAIT_BAR() asm volatile("s_waitcnt vmcnt(0) lgkmcnt(0)\n\ts_barrier" ::: "memory")
; template <int MODE> __device__ __forceinline__ void attn_unit(const Unit& a, char* shm) {
;     ...
;     const bf16_t* ksrc = a.K + (long)lane * a.ldk + wid * 8;
;     const bf16_t* kpsrc = a.KPE + (long)lane * 32 + (wid & 3) * 8;
;     const bf16_t* vsrc = a.V + (long)(16 * (wid & 3) + (lane >> 2)) * a.ldv + (wid >> 2) * 32 + (lane & 3) * 8;
;     const unsigned kdst = lds0 + LDS_K + wid * 1024, kpdst = lds0 + LDS_K + (8 + (wid & 3)) * 1024, vdst = lds0 + LDS_V + wid * 1024;
;     ...
;     const int g = wid >> 2;
;     ATT_DMA(a.t_lo, 0, 0);
;     bf16x8 qr[ND];
;     { const bf16_t* Qw = a.Q + (long)(wid * 32 + r32) * a.ldq + hi * 8;
; #pragma unroll
;       for (int d0 = 0; d0 < ND; ++d0) qr[d0] = *(const bf16x8*)(Qw + d0 * 16); }
;     float mhat = (MODE == 1) ? a.sink2 : 0.f;
;     float l_reg = (MODE == 1 && hi == 0) ? 1.f : 0.f;
;     f32x16 o[2]; o[0] = f32x16{}; o[1] = f32x16{};
;     f32x16 negm;
; #pragma unroll
;     for (int r = 0; r < 16; ++r) negm[r] = -mhat;
;     const int tq0 = a.qpos0 + wid * 32, tq = tq0 + r32;
;     const lds_cptr vp0 = shm3 + LDS_V + ((lane >> 4) & 1) * 32 + (lane & 3) * 8 + (4 * hi + ((lane & 15) >> 2)) * 64;
;     u32x4 pw[4]; pw[0] = (u32x4){0u, 0u, 0u, 0u}; pw[1] = pw[0]; pw[2] = pw[0]; pw[3] = pw[0];
;     bool pend = false; int sv = 0, svp = 0;
;     for (int t = a.t_lo; t < a.t_hi; ++t) {
;         const int s = (t - a.t_lo) & 1;
;         ATT_WAIT_BAR();
;         if (t + 1 < a.t_hi) ATT_DMA(t + 1, s ^ 1, (sv == 2 ? 0 : sv + 1));
.LBB0_1903:
	s_ashr_i32 s3, s2, 31
	s_and_b32 s26, s0, 7
	s_lshl_b64 s[24:25], s[2:3], 11
	s_add_u32 s0, s76, s24
	s_addc_u32 s12, s77, s25
	s_lshl_b32 s15, s26, 8
	s_add_u32 s40, s0, s15
	s_addc_u32 s41, s12, 0
	s_lshl_b64 s[24:25], s[2:3], 6
	v_readlane_b32 s0, v254, 31
	v_mov_b32_e32 v32, v167
	s_add_u32 s30, s0, s24
	v_readlane_b32 s0, v254, 32
	s_addc_u32 s31, s0, s25
	v_readfirstlane_b32 s34, v32
	s_ashr_i32 s25, s34, 6
	s_lshl_b32 s42, s25, 3
	s_and_b32 s15, s25, 3
	v_and_b32_e32 v142, 63, v32
	s_ashr_i32 s43, s42, 31
	s_lshl_b32 s58, s15, 4
	s_lshl_b32 s0, s25, 10
	v_lshlrev_b32_e32 v80, 11, v142
	s_cmp_lg_u32 0, -1
	v_lshl_add_u64 v[0:1], s[40:41], 0, v[80:81]
	v_lshlrev_b32_e32 v80, 6, v142
	s_cselect_b32 s16, 0, 0
	s_lshl_b32 s12, s15, 10
	v_lshl_add_u64 v[34:35], s[42:43], 1, v[0:1]
	v_lshl_add_u64 v[0:1], s[30:31], 0, v[80:81]
	s_add_i32 s31, s16, s12
	s_add_i32 s30, s0, s16
	s_addk_i32 s31, 0x2000
	s_mov_b32 s16, m0
	s_mov_b32 m0, s30
	s_nop 0
	global_load_lds_dwordx4 v[34:35], off
	s_mov_b32 m0, s16
	s_cmp_lt_i32 s25, 4
	v_lshl_add_u64 v[36:37], v[0:1], 0, s[58:59]
	s_cselect_b64 s[42:43], -1, 0
	s_cmp_lt_i32 s25, 4
	s_cbranch_scc1 .LBB0_1905
	s_mov_b32 s16, m0
	s_mov_b32 m0, s31
	s_nop 0
	global_load_lds_dwordx4 v[36:37], off
	s_mov_b32 m0, s16
.LBB0_1905:
	s_lshl_b32 s1, s1, 8
	s_add_u32 s27, s2, s1
	s_addc_u32 s28, s3, 0
	s_mul_i32 s1, s28, 0x600
	s_mul_hi_u32 s2, s27, 0x600
	s_add_i32 s2, s2, s1
	s_mul_i32 s1, s27, 0x600
	s_add_u32 s1, s56, s1
	s_addc_u32 s3, s57, s2
	s_mul_i32 s2, s26, 0xc0
	v_lshlrev_b32_e32 v0, 9, v142
	s_add_u32 s2, s1, s2
	v_and_b32_e32 v0, 0x7800, v0
	s_addc_u32 s3, s3, 0
	v_lshl_or_b32 v80, s15, 15, v0
	s_ashr_i32 s1, s34, 3
	v_lshl_add_u64 v[0:1], s[40:41], 0, v[80:81]
	s_and_b32 s40, s1, 0xffffffe0
	v_lshlrev_b32_e32 v143, 3, v32
	s_ashr_i32 s41, s40, 31
	v_and_b32_e32 v33, 24, v143
	v_lshl_add_u64 v[0:1], s[40:41], 1, v[0:1]
	v_lshlrev_b32_e32 v80, 1, v33
	s_cmp_lg_u32 0, -1
	v_and_b32_e32 v144, 31, v32
	v_lshl_add_u64 v[0:1], v[0:1], 0, v[80:81]
	s_cselect_b32 s1, 0, 0
	s_lshl_b32 s24, s25, 5
	v_lshrrev_b32_e32 v145, 5, v142
	v_lshl_add_u64 v[38:39], v[0:1], 0, s[80:81]
	v_or_b32_e32 v2, s24, v144
	v_mov_b64_e32 v[0:1], s[2:3]
	s_add_i32 s1, s1, s0
	v_mad_i64_i32 v[0:1], s[2:3], v2, s91, v[0:1]
	v_lshlrev_b32_e32 v80, 4, v145
	s_add_i32 s48, s1, 0x6000
	s_mov_b32 s15, m0
	s_mov_b32 m0, s48
	s_nop 0
	global_load_lds_dwordx4 v[38:39], off
	s_mov_b32 m0, s15
	v_lshl_add_u64 v[0:1], v[0:1], 0, v[80:81]
	global_load_dwordx4 v[82:85], v[0:1], off
	global_load_dwordx4 v[86:89], v[0:1], off offset:32
	global_load_dwordx4 v[90:93], v[0:1], off offset:64
	global_load_dwordx4 v[94:97], v[0:1], off offset:96
	global_load_dwordx4 v[98:101], v[0:1], off offset:128
	global_load_dwordx4 v[102:105], v[0:1], off offset:160
	v_lshl_add_u64 v[0:1], v[34:35], 0, s[6:7]
	s_mov_b32 s2, m0
	s_add_i32 s1, s30, 0x3000
	s_mov_b32 m0, s1
	s_nop 0
	global_load_lds_dwordx4 v[0:1], off
	v_lshl_add_u64 v[0:1], v[38:39], 0, s[6:7]
	s_add_i32 s1, s48, 0x2000
	s_mov_b32 m0, s1
	s_nop 0
	global_load_lds_dwordx4 v[0:1], off
	v_cndmask_b32_e64 v0, 0, 1, s[42:43]
	v_cmp_ne_u32_e64 s[40:41], 1, v0
	s_and_b64 vcc, exec, s[42:43]
	s_cbranch_vccnz .Lmla_p1
	v_lshl_add_u64 v[0:1], v[36:37], 0, s[86:87]
	s_add_i32 s1, s31, 0x3000
	s_mov_b32 m0, s1
	s_nop 0
	global_load_lds_dwordx4 v[0:1], off
	s_waitcnt vmcnt(3) lgkmcnt(0)
	s_branch .Lmla_p2

; #define ATT_DMA(t, sk, sv) do { glds16(ksrc + (long)(t) * 64 * a.ldk, (unsigned)__builtin_amdgcn_readfirstlane(kdst + (sk) * KSLOT)); \
;         if (MODE == 0 && wid < 4) glds16(kpsrc + (long)(t) * 64 * 32, (unsigned)__builtin_amdgcn_readfirstlane(kpdst + (sk) * KSLOT)); \
;         glds16(vsrc + (long)(t) * 64 * a.ldv, (unsigned)__builtin_amdgcn_readfirstlane(vdst + (sv) * VSLOT)); } while (0)
; #define ATT_WAIT_BAR() asm volatile("s_waitcnt vmcnt(0) lgkmcnt(0)\n\ts_barrier" ::: "memory")
; template <int MODE> __device__ __forceinline__ void attn_unit(const Unit& a, char* shm) {
;     ...
;     for (int t = a.t_lo; t < a.t_hi; ++t) {
;         const int s = (t - a.t_lo) & 1;
;         ATT_WAIT_BAR();
;         if (t + 1 < a.t_hi) ATT_DMA(t + 1, s ^ 1, (sv == 2 ? 0 : sv + 1));
.Lmla_p2:
	s_barrier
	s_mov_b64 s[0:1], 0x40000
	v_lshl_add_u64 v[0:1], v[34:35], 0, s[0:1]
	s_add_i32 s12, s30, 0x14800
	s_mov_b32 m0, s12
	s_nop 0
	global_load_lds_dwordx4 v[0:1], off
	v_lshl_add_u64 v[0:1], v[38:39], 0, s[0:1]
	s_add_i32 s12, s48, 0x4000
	s_mov_b32 m0, s12
	s_nop 0
	global_load_lds_dwordx4 v[0:1], off
	s_and_b64 vcc, exec, s[42:43]
	s_cbranch_vccnz .LBB0_1907
	s_mov_b64 s[0:1], 0x2000
	v_lshl_add_u64 v[0:1], v[36:37], 0, s[0:1]
	s_add_i32 s12, s31, 0x14800
	s_mov_b32 m0, s12
	s_nop 0
	global_load_lds_dwordx4 v[0:1], off

; #define ATT_DMA(t, sk, sv) do { glds16(ksrc + (long)(t) * 64 * a.ldk, (unsigned)__builtin_amdgcn_readfirstlane(kdst + (sk) * KSLOT)); \
;         if (MODE == 0 && wid < 4) glds16(kpsrc + (long)(t) * 64 * 32, (unsigned)__builtin_amdgcn_readfirstlane(kpdst + (sk) * KSLOT)); \
;         glds16(vsrc + (long)(t) * 64 * a.ldv, (unsigned)__builtin_amdgcn_readfirstlane(vdst + (sv) * VSLOT)); } while (0)
; #define ATT_WAIT_BAR() asm volatile("s_waitcnt vmcnt(0) lgkmcnt(0)\n\ts_barrier" ::: "memory")
; template <int MODE> __device__ __forceinline__ void attn_unit(const Unit& a, char* shm) {
;     ...
;     for (int t = a.t_lo; t < a.t_hi; ++t) {
;         const int s = (t - a.t_lo) & 1;
;         ATT_WAIT_BAR();
;         if (t + 1 < a.t_hi) ATT_DMA(t + 1, s ^ 1, (sv == 2 ? 0 : sv + 1));
.LBB0_1910:
	s_add_i32 s50, s50, 1
	s_mov_b32 s51, s0
	s_and_b64 vcc, exec, s[40:41]
	s_cbranch_vccnz .Lmla_w2
	s_waitcnt vmcnt(2) lgkmcnt(0)
	s_branch .Lmla_wd
.Lmla_w2:
	s_waitcnt vmcnt(3) lgkmcnt(0)

; #define LAS __attribute__((address_space(3)))
; #define ATT_DMA(t, sk, sv) do { glds16(ksrc + (long)(t) * 64 * a.ldk, (unsigned)__builtin_amdgcn_readfirstlane(kdst + (sk) * KSLOT)); \
;         if (MODE == 0 && wid < 4) glds16(kpsrc + (long)(t) * 64 * 32, (unsigned)__builtin_amdgcn_readfirstlane(kpdst + (sk) * KSLOT)); \
;         glds16(vsrc + (long)(t) * 64 * a.ldv, (unsigned)__builtin_amdgcn_readfirstlane(vdst + (sv) * VSLOT)); } while (0)
; template <int MODE> __device__ __forceinline__ void attn_unit(const Unit& a, char* shm) {
;     ...
;         if (t + 1 < a.t_hi) ATT_DMA(t + 1, s ^ 1, (sv == 2 ? 0 : sv + 1));
;         if (pend) { ATT_PV(pw, svp); pend = false; }
;         bool active = true;
;         if (MODE == 1) active = (64 * t + 63 >= tq0 - 128) && (64 * t <= tq0 + 31 + 128);
;         if (active) {
;             const lds_cptr kp = shm3 + LDS_K + s * KSLOT + hi * 1024 + r32 * 16;
;             f32x16 p0 = negm, p1 = negm;
; #pragma unroll
;             for (int d0 = 0; d0 < ND; ++d0) {
;                 const bf16x8 b0 = *(const LAS bf16x8*)(kp + d0 * 2048), b1 = *(const LAS bf16x8*)(kp + d0 * 2048 + 512);
;                 p0 = __builtin_amdgcn_mfma_f32_32x32x16_bf16(b0, qr[d0], p0, 0, 0, 0);
;                 p1 = __builtin_amdgcn_mfma_f32_32x32x16_bf16(b1, qr[d0], p1, 0, 0, 0);
.LBB0_1916:
	s_waitcnt lgkmcnt(11)
	v_mfma_f32_32x32x16_bf16 v[48:63], v[182:185], v[82:85], v[32:47]
	s_add_i32 s1, s0, s30
	s_mov_b32 m0, s1
	s_nop 0
	global_load_lds_dwordx4 v[108:109], off
	s_waitcnt lgkmcnt(10)
	v_mfma_f32_32x32x16_bf16 v[64:79], v[186:189], v[82:85], v[32:47]
	s_andn2_b64 vcc, exec, s[40:41]
	s_cbranch_vccnz .Lmla_nokpe
	s_add_i32 s1, s0, s31
	s_mov_b32 m0, s1
	s_nop 0
	global_load_lds_dwordx4 v[110:111], off
